# weight transpose loop: next tile's 8 global loads now issued right after the current tile's data is copied to a holding register set (before LDS writes/barrier/read-back) so they stay in flight for a
# speedup vs baseline: 1.0095x; 1.0095x over previous
.LBB0_568:
	s_lshr_b32 s4, s36, 8
	v_cvt_f32_u32_e32 v0, s4
	s_sub_i32 s39, 0, s4
	s_abs_i32 s37, s38
	s_ashr_i32 s5, s38, 31
	v_rcp_iflag_f32_e32 v0, v0
	s_nop 0
	v_mul_f32_e32 v0, 0x4f7ffffe, v0
	v_cvt_u32_f32_e32 v0, v0
	s_nop 0
	v_readfirstlane_b32 s40, v0
	s_mul_i32 s39, s39, s40
	s_mul_hi_u32 s39, s40, s39
	s_add_i32 s40, s40, s39
	s_mul_hi_u32 s39, s37, s40
	s_mul_i32 s40, s39, s4
	s_sub_i32 s37, s37, s40
	s_add_i32 s41, s39, 1
	s_sub_i32 s40, s37, s4
	s_cmp_ge_u32 s37, s4
	s_cselect_b32 s39, s41, s39
	s_cselect_b32 s37, s40, s37
	s_add_i32 s40, s39, 1
	s_cmp_ge_u32 s37, s4
	s_cselect_b32 s37, s40, s39
	s_xor_b32 s37, s37, s5
	s_sub_i32 s5, s37, s5
	s_mul_i32 s4, s5, s4
	s_sub_i32 s4, s38, s4
	s_lshl_b32 s4, s4, 8
	s_lshl_b32 s37, s5, 6
	s_ashr_i32 s5, s4, 31
	s_lshl_b64 s[4:5], s[4:5], 2
	s_add_u32 s0, s0, s4
	v_add_u32_e32 v0, s37, v52
	s_addc_u32 s1, s1, s5
	v_add_u32_e32 v8, s37, v39
	v_add_u32_e32 v16, s37, v41
	v_add_u32_e32 v26, s37, v43
	v_ashrrev_i32_e32 v3, 31, v0
	v_lshl_add_u64 v[24:25], s[0:1], 0, v[144:145]
	v_mad_u64_u32 v[0:1], s[0:1], v0, s36, 0
	v_ashrrev_i32_e32 v11, 31, v8
	v_mad_u64_u32 v[8:9], s[0:1], v8, s36, 0
	v_ashrrev_i32_e32 v19, 31, v16
	v_mad_u64_u32 v[16:17], s[0:1], v16, s36, 0
	v_ashrrev_i32_e32 v29, 31, v26
	v_mad_u64_u32 v[26:27], s[0:1], v26, s36, 0
	v_mov_b32_e32 v2, v1
	v_mov_b32_e32 v10, v9
	v_mov_b32_e32 v18, v17
	v_mov_b32_e32 v28, v27
	v_mad_u64_u32 v[2:3], s[0:1], v3, s36, v[2:3]
	v_mad_u64_u32 v[10:11], s[0:1], v11, s36, v[10:11]
	v_mad_u64_u32 v[18:19], s[0:1], v19, s36, v[18:19]
	v_mad_u64_u32 v[28:29], s[0:1], v29, s36, v[28:29]
	v_mov_b32_e32 v1, v2
	v_add_u32_e32 v2, s37, v38
	v_mov_b32_e32 v9, v10
	v_add_u32_e32 v10, s37, v40
	v_mov_b32_e32 v17, v18
	v_add_u32_e32 v18, s37, v42
	v_mov_b32_e32 v27, v28
	v_add_u32_e32 v28, s37, v44
	v_ashrrev_i32_e32 v5, 31, v2
	v_mad_u64_u32 v[2:3], s[0:1], v2, s36, 0
	v_ashrrev_i32_e32 v13, 31, v10
	v_mad_u64_u32 v[10:11], s[0:1], v10, s36, 0
	v_ashrrev_i32_e32 v21, 31, v18
	v_mad_u64_u32 v[18:19], s[0:1], v18, s36, 0
	v_ashrrev_i32_e32 v31, 31, v28
	v_mad_u64_u32 v[28:29], s[0:1], v28, s36, 0
	v_mov_b32_e32 v4, v3
	v_mov_b32_e32 v12, v11
	v_mov_b32_e32 v20, v19
	v_mov_b32_e32 v30, v29
	v_mad_u64_u32 v[4:5], s[0:1], v5, s36, v[4:5]
	v_mad_u64_u32 v[12:13], s[0:1], v13, s36, v[12:13]
	v_mad_u64_u32 v[20:21], s[0:1], v21, s36, v[20:21]
	v_mad_u64_u32 v[30:31], s[0:1], v31, s36, v[30:31]
	v_mov_b32_e32 v3, v4
	v_mov_b32_e32 v11, v12
	v_mov_b32_e32 v19, v20
	v_mov_b32_e32 v29, v30
	v_lshl_add_u64 v[0:1], v[0:1], 2, v[24:25]
	v_lshl_add_u64 v[2:3], v[2:3], 2, v[24:25]
	v_lshl_add_u64 v[8:9], v[8:9], 2, v[24:25]
	v_lshl_add_u64 v[10:11], v[10:11], 2, v[24:25]
	v_lshl_add_u64 v[16:17], v[16:17], 2, v[24:25]
	v_lshl_add_u64 v[18:19], v[18:19], 2, v[24:25]
	v_lshl_add_u64 v[26:27], v[26:27], 2, v[24:25]
	v_lshl_add_u64 v[24:25], v[28:29], 2, v[24:25]
	global_load_dwordx4 v[4:7], v[0:1], off nt
	s_nop 0
	global_load_dwordx4 v[0:3], v[2:3], off nt
	s_nop 0
	global_load_dwordx4 v[12:15], v[8:9], off nt
	s_nop 0
	global_load_dwordx4 v[8:11], v[10:11], off nt
	s_nop 0
	global_load_dwordx4 v[20:23], v[16:17], off nt
	s_nop 0
	global_load_dwordx4 v[16:19], v[18:19], off nt
	s_nop 0
	global_load_dwordx4 v[28:31], v[26:27], off nt
	s_nop 0
	global_load_dwordx4 v[24:27], v[24:25], off nt
	s_branch .Ltr_wr

.LBB0_594:
	s_add_i32 s15, s15, s55
	s_add_i32 s0, s54, s14
	s_cmp_ge_i32 s0, s8
	s_waitcnt vmcnt(0)
	v_mov_b64_e32 v[188:189], v[0:1]
	v_mov_b64_e32 v[190:191], v[2:3]
	v_mov_b64_e32 v[192:193], v[4:5]
	v_mov_b64_e32 v[194:195], v[6:7]
	v_mov_b64_e32 v[196:197], v[8:9]
	v_mov_b64_e32 v[198:199], v[10:11]
	v_mov_b64_e32 v[200:201], v[12:13]
	v_mov_b64_e32 v[202:203], v[14:15]
	v_mov_b64_e32 v[204:205], v[16:17]
	v_mov_b64_e32 v[206:207], v[18:19]
	v_mov_b64_e32 v[208:209], v[20:21]
	v_mov_b64_e32 v[210:211], v[22:23]
	v_mov_b64_e32 v[212:213], v[24:25]
	v_mov_b64_e32 v[214:215], v[26:27]
	v_mov_b64_e32 v[216:217], v[28:29]
	v_mov_b64_e32 v[218:219], v[30:31]
	s_cbranch_scc1 .Ltr_wr
	s_branch .Ltr_next
.Ltr_wr:
	ds_write2_b32 v51, v192, v193 offset1:1
	ds_write2_b32 v51, v194, v195 offset0:2 offset1:3
	ds_write2_b32 v53, v188, v189 offset1:1
	ds_write2_b32 v53, v190, v191 offset0:2 offset1:3
	ds_write2_b32 v54, v200, v201 offset1:1
	ds_write2_b32 v54, v202, v203 offset0:2 offset1:3
	ds_write2_b32 v55, v196, v197 offset1:1
	ds_write2_b32 v55, v198, v199 offset0:2 offset1:3
	ds_write2_b32 v56, v208, v209 offset1:1
	ds_write2_b32 v56, v210, v211 offset0:2 offset1:3
	ds_write2_b32 v57, v204, v205 offset1:1
	ds_write2_b32 v57, v206, v207 offset0:2 offset1:3
	ds_write2_b32 v58, v216, v217 offset1:1
	ds_write2_b32 v58, v218, v219 offset0:2 offset1:3
	ds_write2_b32 v59, v212, v213 offset1:1
	ds_write2_b32 v59, v214, v215 offset0:2 offset1:3
	s_waitcnt lgkmcnt(0)
	s_barrier
	s_branch .LBB0_569
.Ltr_next:
	s_cmp_ge_i32 s0, s48
	s_mov_b64 s[0:1], -1
	s_cbranch_scc0 .LBB0_605
	s_sub_i32 s4, s15, s48
	s_add_i32 s0, s54, s12
	s_cmp_ge_i32 s0, s51
	s_mov_b64 s[0:1], -1
	s_cbranch_scc0 .LBB0_602
	s_add_i32 s0, s54, s13
	s_cmp_ge_i32 s0, s53
	s_mov_b64 s[0:1], -1
	s_cbranch_scc0 .LBB0_599
	s_add_i32 s37, s54, s11
	s_mov_b64 s[0:1], 0
